# GEMM1 epilogue: plain (non-GLU) tiles dispatch once into a branch-free straight-line trace of the 16 row-group blocks (GLU blocks and 31 uniform branches removed from that path)
# speedup vs baseline: 1.0037x; 1.0037x over previous
; __device__ __forceinline__ unsigned cvt_pk_bf16(float lo, float hi) { return ::pk2(lo, hi); }
;     __device__ __forceinline__ void operator()(const f32x4 (&acc)[2][2][4][2], const Pre& p, const Unit& u, int wr, int wc, int fr, int fq) const {
;         asm volatile("" : "+v"(fr), "+v"(fq));
;         const int row0 = u.pm * BM + wr * 64 + fr, col0 = u.pn * BM + wc * 32 + 8 * fq;
;         const bool glu = (u.pn * BM >= ZB) && (u.pn * BM < ZQ);
; #pragma unroll
;         for (int ai = 0; ai < 2; ++ai)
; #pragma unroll
;             for (int m = 0; m < 4; ++m) { bf16_t* rowp = O + (size_t)(row0 + ai * HALF + m * 16) * ldc;
;                 const float rs = p.rs[ai * 4 + m];
; #pragma unroll
;                 for (int bj = 0; bj < 2; ++bj) {
;                     const f32x4 v0 = (__builtin_convertvector(__builtin_bit_cast(i32x4, acc[ai][bj][m][0]), f32x4) * p.wv[bj][0]) * rs, v1 = (__builtin_convertvector(__builtin_bit_cast(i32x4, acc[ai][bj][m][1]), f32x4) * p.wv[bj][1]) * rs;
;                     if (glu) {
;                         const float o0 = v0[0] * __builtin_amdgcn_rcpf(1.f + __builtin_amdgcn_exp2f(v0[1] * -1.44269504f)), o1 = v0[2] * __builtin_amdgcn_rcpf(1.f + __builtin_amdgcn_exp2f(v0[3] * -1.44269504f));
;                         const float o2 = v1[0] * __builtin_amdgcn_rcpf(1.f + __builtin_amdgcn_exp2f(v1[1] * -1.44269504f)), o3 = v1[2] * __builtin_amdgcn_rcpf(1.f + __builtin_amdgcn_exp2f(v1[3] * -1.44269504f));
;                         u32x2 w; w.x = cvt_pk_bf16(o0, o1); w.y = cvt_pk_bf16(o2, o3);
;                         *(u32x2*)(rowp + ZB + ((col0 + bj * HALF - ZB) >> 1)) = w;
;                     } else {
;                         u32x4 w; w.x = cvt_pk_bf16(v0[0], v0[1]); w.y = cvt_pk_bf16(v0[2], v0[3]); w.z = cvt_pk_bf16(v1[0], v1[1]); w.w = cvt_pk_bf16(v1[2], v1[3]);
;                         *(u32x4*)(rowp + col0 + bj * HALF) = w; } } }
.Lg1plain_0:
	v_cvt_pk_bf16_f32 v156, v148, v149
	v_cvt_pk_bf16_f32 v157, v140, v141
	v_cvt_pk_bf16_f32 v158, v150, v151
	v_cvt_pk_bf16_f32 v159, v152, v153
	global_store_dwordx4 v[144:145], v[156:159], off
	s_mov_b64 s[2:3], 0
	v_add_u32_e32 v138, 0xffffff00, v146
	v_ashrrev_i32_e32 v138, 1, v138
	s_andn2_b64 vcc, exec, s[2:3]
	v_ashrrev_i32_e32 v139, 31, v138
	v_cvt_f32_i32_e32 v135, v135
	v_cvt_f32_i32_e32 v134, v134
	v_cvt_f32_i32_e32 v137, v137
	v_cvt_f32_i32_e32 v136, v136
	v_cvt_f32_i32_e32 v151, v133
	v_cvt_f32_i32_e32 v150, v132
	v_cvt_f32_i32_e32 v149, v131
	v_cvt_f32_i32_e32 v148, v130
	v_mov_b32_e32 v227, v226
	v_pk_mul_f32 v[134:135], v[14:15], v[134:135]
	v_pk_mul_f32 v[136:137], v[16:17], v[136:137]
	v_mov_b32_e32 v140, v226
	v_mov_b32_e32 v141, v226
	v_pk_mul_f32 v[132:133], v[134:135], v[226:227]
	v_pk_mul_f32 v[134:135], v[12:13], v[150:151]
	v_pk_mul_f32 v[130:131], v[136:137], v[140:141]
	v_pk_mul_f32 v[148:149], v[10:11], v[148:149]
	v_pk_mul_f32 v[136:137], v[134:135], v[140:141]
	v_cndmask_b32_e64 v140, 0, 1, s[0:1]
	v_pk_mul_f32 v[134:135], v[148:149], v[226:227]
	v_cmp_ne_u32_e64 s[6:7], 1, v140
	s_andn2_b64 vcc, exec, s[0:1]
	s_mov_b64 s[0:1], -1
	v_cvt_pk_bf16_f32 v148, v132, v133
	v_cvt_pk_bf16_f32 v149, v130, v131
	v_cvt_pk_bf16_f32 v150, v134, v135
	v_cvt_pk_bf16_f32 v151, v136, v137
	s_mov_b64 s[0:1], 0
	global_store_dwordx4 v[144:145], v[148:151], off offset:256
	s_andn2_b64 vcc, exec, s[0:1]
	v_add_u32_e32 v140, 0xffffff80, v146
	v_cvt_f32_i32_e32 v135, v129
	v_cvt_f32_i32_e32 v134, v128
	v_add_u32_e32 v136, 16, v154
	v_mov_b64_e32 v[130:131], s[28:29]
	v_cvt_f32_i32_e32 v133, v127
	v_cvt_f32_i32_e32 v132, v126
	v_mad_i64_i32 v[126:127], s[0:1], v136, s78, v[130:131]
	v_pk_mul_f32 v[130:131], v[8:9], v[134:135]
	v_cvt_f32_i32_e32 v135, v123
	v_cvt_f32_i32_e32 v137, v125
	v_cvt_f32_i32_e32 v136, v124
	v_cvt_f32_i32_e32 v134, v122
	v_pk_mul_f32 v[132:133], v[6:7], v[132:133]
	v_pk_mul_f32 v[122:123], v[130:131], v[228:229] op_sel_hi:[1,0]
	v_pk_mul_f32 v[130:131], v[4:5], v[136:137]
	v_pk_mul_f32 v[134:135], v[2:3], v[134:135]
	v_lshl_add_u64 v[128:129], v[146:147], 1, v[126:127]
	v_pk_mul_f32 v[124:125], v[132:133], v[228:229] op_sel_hi:[1,0]
	v_pk_mul_f32 v[132:133], v[130:131], v[228:229] op_sel_hi:[1,0]
	v_pk_mul_f32 v[130:131], v[134:135], v[228:229] op_sel_hi:[1,0]
	s_and_b64 vcc, exec, s[6:7]
	s_mov_b64 s[0:1], -1
	v_cvt_pk_bf16_f32 v134, v124, v125
	v_cvt_pk_bf16_f32 v135, v122, v123
	v_cvt_pk_bf16_f32 v136, v130, v131
	v_cvt_pk_bf16_f32 v137, v132, v133
	s_mov_b64 s[0:1], 0
	global_store_dwordx4 v[128:129], v[134:137], off
	s_andn2_b64 vcc, exec, s[0:1]
	v_cvt_f32_i32_e32 v119, v119
	v_cvt_f32_i32_e32 v118, v118
	v_cvt_f32_i32_e32 v121, v121
	v_cvt_f32_i32_e32 v120, v120
	v_cvt_f32_i32_e32 v125, v115
	v_cvt_f32_i32_e32 v131, v117
	v_cvt_f32_i32_e32 v130, v116
	v_cvt_f32_i32_e32 v124, v114
	v_mov_b32_e32 v229, v228
	v_pk_mul_f32 v[118:119], v[14:15], v[118:119]
	v_pk_mul_f32 v[120:121], v[16:17], v[120:121]
	v_mov_b32_e32 v122, v228
	v_mov_b32_e32 v123, v228
	v_pk_mul_f32 v[116:117], v[118:119], v[228:229]
	v_pk_mul_f32 v[118:119], v[12:13], v[130:131]
	v_pk_mul_f32 v[124:125], v[10:11], v[124:125]
	v_pk_mul_f32 v[114:115], v[120:121], v[122:123]
	v_pk_mul_f32 v[120:121], v[118:119], v[122:123]
	v_pk_mul_f32 v[118:119], v[124:125], v[228:229]
	s_and_b64 vcc, exec, s[6:7]
	s_mov_b64 s[0:1], -1
	v_cvt_pk_bf16_f32 v122, v116, v117
	v_cvt_pk_bf16_f32 v123, v114, v115
	v_cvt_pk_bf16_f32 v124, v118, v119
	v_cvt_pk_bf16_f32 v125, v120, v121
	s_mov_b64 s[0:1], 0
	global_store_dwordx4 v[128:129], v[122:125], off offset:256
	s_andn2_b64 vcc, exec, s[0:1]
	v_cvt_f32_i32_e32 v119, v113
	v_cvt_f32_i32_e32 v118, v112
	v_add_u32_e32 v120, 32, v154
	v_mov_b64_e32 v[114:115], s[28:29]
	v_cvt_f32_i32_e32 v117, v111
	v_cvt_f32_i32_e32 v116, v110
	v_mad_i64_i32 v[110:111], s[0:1], v120, s78, v[114:115]
	v_pk_mul_f32 v[114:115], v[8:9], v[118:119]
	v_cvt_f32_i32_e32 v119, v107
	v_cvt_f32_i32_e32 v121, v109
	v_cvt_f32_i32_e32 v120, v108
	v_cvt_f32_i32_e32 v118, v106
	v_pk_mul_f32 v[116:117], v[6:7], v[116:117]
	v_pk_mul_f32 v[106:107], v[114:115], v[230:231] op_sel_hi:[1,0]
	v_pk_mul_f32 v[114:115], v[4:5], v[120:121]
	v_pk_mul_f32 v[118:119], v[2:3], v[118:119]
	v_lshl_add_u64 v[112:113], v[146:147], 1, v[110:111]
	v_pk_mul_f32 v[108:109], v[116:117], v[230:231] op_sel_hi:[1,0]
	v_pk_mul_f32 v[116:117], v[114:115], v[230:231] op_sel_hi:[1,0]
	v_pk_mul_f32 v[114:115], v[118:119], v[230:231] op_sel_hi:[1,0]
	s_and_b64 vcc, exec, s[6:7]
	s_mov_b64 s[0:1], -1
	v_cvt_pk_bf16_f32 v118, v108, v109
	v_cvt_pk_bf16_f32 v119, v106, v107
	v_cvt_pk_bf16_f32 v120, v114, v115
	v_cvt_pk_bf16_f32 v121, v116, v117
	s_mov_b64 s[0:1], 0
	global_store_dwordx4 v[112:113], v[118:121], off
	s_andn2_b64 vcc, exec, s[0:1]
	v_cvt_f32_i32_e32 v103, v103
	v_cvt_f32_i32_e32 v102, v102
	v_cvt_f32_i32_e32 v105, v105
	v_cvt_f32_i32_e32 v104, v104
	v_cvt_f32_i32_e32 v109, v99
	v_cvt_f32_i32_e32 v115, v101
	v_cvt_f32_i32_e32 v114, v100
	v_cvt_f32_i32_e32 v108, v98
	v_mov_b32_e32 v231, v230
	v_pk_mul_f32 v[102:103], v[14:15], v[102:103]
	v_pk_mul_f32 v[104:105], v[16:17], v[104:105]
	v_mov_b32_e32 v106, v230
	v_mov_b32_e32 v107, v230
	v_pk_mul_f32 v[100:101], v[102:103], v[230:231]
	v_pk_mul_f32 v[102:103], v[12:13], v[114:115]
	v_pk_mul_f32 v[108:109], v[10:11], v[108:109]
	v_pk_mul_f32 v[98:99], v[104:105], v[106:107]
	v_pk_mul_f32 v[104:105], v[102:103], v[106:107]
	v_pk_mul_f32 v[102:103], v[108:109], v[230:231]
	s_and_b64 vcc, exec, s[6:7]
	s_mov_b64 s[0:1], -1
	v_cvt_pk_bf16_f32 v106, v100, v101
	v_cvt_pk_bf16_f32 v107, v98, v99
; __device__ __forceinline__ unsigned cvt_pk_bf16(float lo, float hi) { return ::pk2(lo, hi); }
;     __device__ __forceinline__ void operator()(const f32x4 (&acc)[2][2][4][2], const Pre& p, const Unit& u, int wr, int wc, int fr, int fq) const {
;         asm volatile("" : "+v"(fr), "+v"(fq));
;         const int row0 = u.pm * BM + wr * 64 + fr, col0 = u.pn * BM + wc * 32 + 8 * fq;
;         const bool glu = (u.pn * BM >= ZB) && (u.pn * BM < ZQ);
; #pragma unroll
;         for (int ai = 0; ai < 2; ++ai)
; #pragma unroll
;             for (int m = 0; m < 4; ++m) { bf16_t* rowp = O + (size_t)(row0 + ai * HALF + m * 16) * ldc;
;                 const float rs = p.rs[ai * 4 + m];
; #pragma unroll
;                 for (int bj = 0; bj < 2; ++bj) {
;                     const f32x4 v0 = (__builtin_convertvector(__builtin_bit_cast(i32x4, acc[ai][bj][m][0]), f32x4) * p.wv[bj][0]) * rs, v1 = (__builtin_convertvector(__builtin_bit_cast(i32x4, acc[ai][bj][m][1]), f32x4) * p.wv[bj][1]) * rs;
;                     if (glu) {
;                         const float o0 = v0[0] * __builtin_amdgcn_rcpf(1.f + __builtin_amdgcn_exp2f(v0[1] * -1.44269504f)), o1 = v0[2] * __builtin_amdgcn_rcpf(1.f + __builtin_amdgcn_exp2f(v0[3] * -1.44269504f));
;                         const float o2 = v1[0] * __builtin_amdgcn_rcpf(1.f + __builtin_amdgcn_exp2f(v1[1] * -1.44269504f)), o3 = v1[2] * __builtin_amdgcn_rcpf(1.f + __builtin_amdgcn_exp2f(v1[3] * -1.44269504f));
;                         u32x2 w; w.x = cvt_pk_bf16(o0, o1); w.y = cvt_pk_bf16(o2, o3);
;                         *(u32x2*)(rowp + ZB + ((col0 + bj * HALF - ZB) >> 1)) = w;
;                     } else {
;                         u32x4 w; w.x = cvt_pk_bf16(v0[0], v0[1]); w.y = cvt_pk_bf16(v0[2], v0[3]); w.z = cvt_pk_bf16(v1[0], v1[1]); w.w = cvt_pk_bf16(v1[2], v1[3]);
;                         *(u32x4*)(rowp + col0 + bj * HALF) = w; } } }
	v_cvt_pk_bf16_f32 v108, v102, v103
	v_cvt_pk_bf16_f32 v109, v104, v105
	s_mov_b64 s[0:1], 0
	global_store_dwordx4 v[112:113], v[106:109], off offset:256
	s_andn2_b64 vcc, exec, s[0:1]
	v_cvt_f32_i32_e32 v103, v97
	v_cvt_f32_i32_e32 v102, v96
	v_add_u32_e32 v104, 48, v154
	v_mov_b64_e32 v[98:99], s[28:29]
	v_cvt_f32_i32_e32 v101, v95
	v_cvt_f32_i32_e32 v100, v94
	v_mad_i64_i32 v[94:95], s[0:1], v104, s78, v[98:99]
	v_pk_mul_f32 v[98:99], v[8:9], v[102:103]
	v_cvt_f32_i32_e32 v103, v91
	v_cvt_f32_i32_e32 v105, v93
	v_cvt_f32_i32_e32 v104, v92
	v_cvt_f32_i32_e32 v102, v90
	v_pk_mul_f32 v[100:101], v[6:7], v[100:101]
	v_pk_mul_f32 v[90:91], v[98:99], v[232:233] op_sel_hi:[1,0]
	v_pk_mul_f32 v[98:99], v[4:5], v[104:105]
	v_pk_mul_f32 v[102:103], v[2:3], v[102:103]
	v_lshl_add_u64 v[96:97], v[146:147], 1, v[94:95]
	v_pk_mul_f32 v[92:93], v[100:101], v[232:233] op_sel_hi:[1,0]
	v_pk_mul_f32 v[100:101], v[98:99], v[232:233] op_sel_hi:[1,0]
	v_pk_mul_f32 v[98:99], v[102:103], v[232:233] op_sel_hi:[1,0]
	s_and_b64 vcc, exec, s[6:7]
	s_mov_b64 s[0:1], -1
	v_cvt_pk_bf16_f32 v102, v92, v93
	v_cvt_pk_bf16_f32 v103, v90, v91
	v_cvt_pk_bf16_f32 v104, v98, v99
	v_cvt_pk_bf16_f32 v105, v100, v101
	s_mov_b64 s[0:1], 0
	global_store_dwordx4 v[96:97], v[102:105], off
	s_andn2_b64 vcc, exec, s[0:1]
	v_cvt_f32_i32_e32 v87, v87
	v_cvt_f32_i32_e32 v86, v86
	v_cvt_f32_i32_e32 v89, v89
	v_cvt_f32_i32_e32 v88, v88
	v_cvt_f32_i32_e32 v93, v83
	v_cvt_f32_i32_e32 v99, v85
	v_cvt_f32_i32_e32 v98, v84
	v_cvt_f32_i32_e32 v92, v82
	v_mov_b32_e32 v233, v232
	v_pk_mul_f32 v[86:87], v[14:15], v[86:87]
	v_pk_mul_f32 v[88:89], v[16:17], v[88:89]
	v_mov_b32_e32 v90, v232
	v_mov_b32_e32 v91, v232
	v_pk_mul_f32 v[84:85], v[86:87], v[232:233]
	v_pk_mul_f32 v[86:87], v[12:13], v[98:99]
	v_pk_mul_f32 v[92:93], v[10:11], v[92:93]
	v_pk_mul_f32 v[82:83], v[88:89], v[90:91]
	v_pk_mul_f32 v[88:89], v[86:87], v[90:91]
	v_pk_mul_f32 v[86:87], v[92:93], v[232:233]
	s_and_b64 vcc, exec, s[6:7]
	s_mov_b64 s[0:1], -1
	v_cvt_pk_bf16_f32 v90, v84, v85
	v_cvt_pk_bf16_f32 v91, v82, v83
	v_cvt_pk_bf16_f32 v92, v86, v87
	v_cvt_pk_bf16_f32 v93, v88, v89
	s_mov_b64 s[0:1], 0
	global_store_dwordx4 v[96:97], v[90:93], off offset:256
	s_andn2_b64 vcc, exec, s[0:1]
	v_cvt_f32_i32_e32 v87, v81
	v_cvt_f32_i32_e32 v86, v80
	v_add_u32_e32 v88, 0x80, v154
	v_mov_b64_e32 v[82:83], s[28:29]
	v_cvt_f32_i32_e32 v85, v79
	v_cvt_f32_i32_e32 v84, v78
	v_mad_i64_i32 v[78:79], s[0:1], v88, s78, v[82:83]
	v_pk_mul_f32 v[82:83], v[8:9], v[86:87]
	v_cvt_f32_i32_e32 v87, v75
	v_cvt_f32_i32_e32 v89, v77
	v_cvt_f32_i32_e32 v88, v76
	v_cvt_f32_i32_e32 v86, v74
	v_pk_mul_f32 v[84:85], v[6:7], v[84:85]
	v_pk_mul_f32 v[74:75], v[82:83], v[234:235] op_sel_hi:[1,0]
	v_pk_mul_f32 v[82:83], v[4:5], v[88:89]
	v_pk_mul_f32 v[86:87], v[2:3], v[86:87]
	v_lshl_add_u64 v[80:81], v[146:147], 1, v[78:79]
	v_pk_mul_f32 v[76:77], v[84:85], v[234:235] op_sel_hi:[1,0]
	v_pk_mul_f32 v[84:85], v[82:83], v[234:235] op_sel_hi:[1,0]
	v_pk_mul_f32 v[82:83], v[86:87], v[234:235] op_sel_hi:[1,0]
	s_and_b64 vcc, exec, s[6:7]
	s_mov_b64 s[0:1], -1
	v_cvt_pk_bf16_f32 v86, v76, v77
	v_cvt_pk_bf16_f32 v87, v74, v75
	v_cvt_pk_bf16_f32 v88, v82, v83
	v_cvt_pk_bf16_f32 v89, v84, v85
	s_mov_b64 s[0:1], 0
	global_store_dwordx4 v[80:81], v[86:89], off
	s_andn2_b64 vcc, exec, s[0:1]
	v_cvt_f32_i32_e32 v71, v71
	v_cvt_f32_i32_e32 v70, v70
	v_cvt_f32_i32_e32 v73, v73
	v_cvt_f32_i32_e32 v72, v72
	v_cvt_f32_i32_e32 v83, v67
	v_cvt_f32_i32_e32 v85, v69
	v_cvt_f32_i32_e32 v84, v68
	v_cvt_f32_i32_e32 v82, v66
	v_mov_b32_e32 v74, v234
	v_mov_b32_e32 v75, v234
	v_pk_mul_f32 v[70:71], v[14:15], v[70:71]
	v_pk_mul_f32 v[72:73], v[16:17], v[72:73]
	v_mov_b32_e32 v76, v234
	v_mov_b32_e32 v77, v234
	v_pk_mul_f32 v[68:69], v[70:71], v[74:75]
	v_pk_mul_f32 v[70:71], v[12:13], v[84:85]
	v_pk_mul_f32 v[82:83], v[10:11], v[82:83]
	v_pk_mul_f32 v[66:67], v[72:73], v[76:77]
	v_pk_mul_f32 v[72:73], v[70:71], v[76:77]
	v_pk_mul_f32 v[70:71], v[82:83], v[74:75]
	s_and_b64 vcc, exec, s[6:7]
	s_mov_b64 s[0:1], -1
	v_cvt_pk_bf16_f32 v74, v68, v69
	v_cvt_pk_bf16_f32 v75, v66, v67
	v_cvt_pk_bf16_f32 v76, v70, v71
	v_cvt_pk_bf16_f32 v77, v72, v73
	s_mov_b64 s[0:1], 0
	global_store_dwordx4 v[80:81], v[74:77], off offset:256
	s_andn2_b64 vcc, exec, s[0:1]
	v_cvt_f32_i32_e32 v71, v65
	v_cvt_f32_i32_e32 v70, v64
	v_add_u32_e32 v72, 0x90, v154
	v_mov_b64_e32 v[66:67], s[28:29]
	v_cvt_f32_i32_e32 v69, v63
	v_cvt_f32_i32_e32 v68, v62
	v_mad_i64_i32 v[62:63], s[0:1], v72, s78, v[66:67]
	v_pk_mul_f32 v[66:67], v[8:9], v[70:71]
	v_cvt_f32_i32_e32 v71, v59
	v_cvt_f32_i32_e32 v73, v61
	v_cvt_f32_i32_e32 v72, v60
	v_cvt_f32_i32_e32 v70, v58
	v_pk_mul_f32 v[68:69], v[6:7], v[68:69]
	v_pk_mul_f32 v[58:59], v[66:67], v[234:235] op_sel:[0,1]
	v_pk_mul_f32 v[66:67], v[4:5], v[72:73]
	v_pk_mul_f32 v[70:71], v[2:3], v[70:71]
	v_lshl_add_u64 v[64:65], v[146:147], 1, v[62:63]
	v_pk_mul_f32 v[60:61], v[68:69], v[234:235] op_sel:[0,1]
	v_pk_mul_f32 v[68:69], v[66:67], v[234:235] op_sel:[0,1]
	v_pk_mul_f32 v[66:67], v[70:71], v[234:235] op_sel:[0,1]
	s_and_b64 vcc, exec, s[6:7]
	s_mov_b64 s[0:1], -1
	v_cvt_pk_bf16_f32 v70, v60, v61
	v_cvt_pk_bf16_f32 v71, v58, v59
; __device__ __forceinline__ unsigned cvt_pk_bf16(float lo, float hi) { return ::pk2(lo, hi); }
;     __device__ __forceinline__ void operator()(const f32x4 (&acc)[2][2][4][2], const Pre& p, const Unit& u, int wr, int wc, int fr, int fq) const {
;         asm volatile("" : "+v"(fr), "+v"(fq));
;         const int row0 = u.pm * BM + wr * 64 + fr, col0 = u.pn * BM + wc * 32 + 8 * fq;
;         const bool glu = (u.pn * BM >= ZB) && (u.pn * BM < ZQ);
; #pragma unroll
;         for (int ai = 0; ai < 2; ++ai)
; #pragma unroll
;             for (int m = 0; m < 4; ++m) { bf16_t* rowp = O + (size_t)(row0 + ai * HALF + m * 16) * ldc;
;                 const float rs = p.rs[ai * 4 + m];
; #pragma unroll
;                 for (int bj = 0; bj < 2; ++bj) {
;                     const f32x4 v0 = (__builtin_convertvector(__builtin_bit_cast(i32x4, acc[ai][bj][m][0]), f32x4) * p.wv[bj][0]) * rs, v1 = (__builtin_convertvector(__builtin_bit_cast(i32x4, acc[ai][bj][m][1]), f32x4) * p.wv[bj][1]) * rs;
;                     if (glu) {
;                         const float o0 = v0[0] * __builtin_amdgcn_rcpf(1.f + __builtin_amdgcn_exp2f(v0[1] * -1.44269504f)), o1 = v0[2] * __builtin_amdgcn_rcpf(1.f + __builtin_amdgcn_exp2f(v0[3] * -1.44269504f));
;                         const float o2 = v1[0] * __builtin_amdgcn_rcpf(1.f + __builtin_amdgcn_exp2f(v1[1] * -1.44269504f)), o3 = v1[2] * __builtin_amdgcn_rcpf(1.f + __builtin_amdgcn_exp2f(v1[3] * -1.44269504f));
;                         u32x2 w; w.x = cvt_pk_bf16(o0, o1); w.y = cvt_pk_bf16(o2, o3);
;                         *(u32x2*)(rowp + ZB + ((col0 + bj * HALF - ZB) >> 1)) = w;
;                     } else {
;                         u32x4 w; w.x = cvt_pk_bf16(v0[0], v0[1]); w.y = cvt_pk_bf16(v0[2], v0[3]); w.z = cvt_pk_bf16(v1[0], v1[1]); w.w = cvt_pk_bf16(v1[2], v1[3]);
;                         *(u32x4*)(rowp + col0 + bj * HALF) = w; } } }
	v_cvt_pk_bf16_f32 v72, v66, v67
	v_cvt_pk_bf16_f32 v73, v68, v69
	s_mov_b64 s[0:1], 0
	global_store_dwordx4 v[64:65], v[70:73], off
	s_andn2_b64 vcc, exec, s[0:1]
	v_cvt_f32_i32_e32 v55, v55
	v_cvt_f32_i32_e32 v54, v54
	v_cvt_f32_i32_e32 v57, v57
	v_cvt_f32_i32_e32 v56, v56
	v_cvt_f32_i32_e32 v67, v51
	v_cvt_f32_i32_e32 v69, v53
	v_cvt_f32_i32_e32 v68, v52
	v_cvt_f32_i32_e32 v66, v50
	v_mov_b32_e32 v58, v235
	v_mov_b32_e32 v59, v235
	v_pk_mul_f32 v[54:55], v[14:15], v[54:55]
	v_pk_mul_f32 v[56:57], v[16:17], v[56:57]
	v_mov_b32_e32 v60, v235
	v_mov_b32_e32 v61, v235
	v_pk_mul_f32 v[52:53], v[54:55], v[58:59]
	v_pk_mul_f32 v[54:55], v[12:13], v[68:69]
	v_pk_mul_f32 v[66:67], v[10:11], v[66:67]
	v_pk_mul_f32 v[50:51], v[56:57], v[60:61]
	v_pk_mul_f32 v[56:57], v[54:55], v[60:61]
	v_pk_mul_f32 v[54:55], v[66:67], v[58:59]
	s_and_b64 vcc, exec, s[6:7]
	s_mov_b64 s[0:1], -1
	v_cvt_pk_bf16_f32 v58, v52, v53
	v_cvt_pk_bf16_f32 v59, v50, v51
	v_cvt_pk_bf16_f32 v60, v54, v55
	v_cvt_pk_bf16_f32 v61, v56, v57
	s_mov_b64 s[0:1], 0
	global_store_dwordx4 v[64:65], v[58:61], off offset:256
	s_andn2_b64 vcc, exec, s[0:1]
	v_cvt_f32_i32_e32 v55, v49
	v_cvt_f32_i32_e32 v54, v48
	v_add_u32_e32 v56, 0xa0, v154
	v_mov_b64_e32 v[50:51], s[28:29]
	v_cvt_f32_i32_e32 v53, v47
	v_cvt_f32_i32_e32 v52, v46
	v_mad_i64_i32 v[46:47], s[0:1], v56, s78, v[50:51]
	v_pk_mul_f32 v[50:51], v[8:9], v[54:55]
	v_cvt_f32_i32_e32 v55, v43
	v_cvt_f32_i32_e32 v57, v45
	v_cvt_f32_i32_e32 v56, v44
	v_cvt_f32_i32_e32 v54, v42
	v_pk_mul_f32 v[52:53], v[6:7], v[52:53]
	v_pk_mul_f32 v[42:43], v[50:51], v[236:237] op_sel_hi:[1,0]
	v_pk_mul_f32 v[50:51], v[4:5], v[56:57]
	v_pk_mul_f32 v[54:55], v[2:3], v[54:55]
	v_lshl_add_u64 v[48:49], v[146:147], 1, v[46:47]
	v_pk_mul_f32 v[44:45], v[52:53], v[236:237] op_sel_hi:[1,0]
	v_pk_mul_f32 v[52:53], v[50:51], v[236:237] op_sel_hi:[1,0]
	v_pk_mul_f32 v[50:51], v[54:55], v[236:237] op_sel_hi:[1,0]
	s_and_b64 vcc, exec, s[6:7]
	s_mov_b64 s[0:1], -1
	v_cvt_pk_bf16_f32 v54, v44, v45
	v_cvt_pk_bf16_f32 v55, v42, v43
	v_cvt_pk_bf16_f32 v56, v50, v51
	v_cvt_pk_bf16_f32 v57, v52, v53
	s_mov_b64 s[0:1], 0
	global_store_dwordx4 v[48:49], v[54:57], off
	s_andn2_b64 vcc, exec, s[0:1]
	v_cvt_f32_i32_e32 v39, v39
	v_cvt_f32_i32_e32 v38, v38
	v_cvt_f32_i32_e32 v41, v41
	v_cvt_f32_i32_e32 v40, v40
	v_cvt_f32_i32_e32 v51, v35
	v_cvt_f32_i32_e32 v53, v37
	v_cvt_f32_i32_e32 v52, v36
	v_cvt_f32_i32_e32 v50, v34
	v_mov_b32_e32 v42, v236
	v_mov_b32_e32 v43, v236
	v_pk_mul_f32 v[38:39], v[14:15], v[38:39]
	v_pk_mul_f32 v[40:41], v[16:17], v[40:41]
	v_mov_b32_e32 v44, v236
	v_mov_b32_e32 v45, v236
	v_pk_mul_f32 v[36:37], v[38:39], v[42:43]
	v_pk_mul_f32 v[38:39], v[12:13], v[52:53]
	v_pk_mul_f32 v[50:51], v[10:11], v[50:51]
	v_pk_mul_f32 v[34:35], v[40:41], v[44:45]
	v_pk_mul_f32 v[40:41], v[38:39], v[44:45]
	v_pk_mul_f32 v[38:39], v[50:51], v[42:43]
	s_and_b64 vcc, exec, s[6:7]
	s_mov_b64 s[0:1], -1
	v_cvt_pk_bf16_f32 v42, v36, v37
	v_cvt_pk_bf16_f32 v43, v34, v35
	v_cvt_pk_bf16_f32 v44, v38, v39
	v_cvt_pk_bf16_f32 v45, v40, v41
	s_mov_b64 s[0:1], 0
	global_store_dwordx4 v[48:49], v[42:45], off offset:256
	s_andn2_b64 vcc, exec, s[0:1]
	v_add_u32_e32 v40, 0xb0, v154
	v_mov_b64_e32 v[34:35], s[28:29]
	v_cvt_f32_i32_e32 v39, v33
	v_cvt_f32_i32_e32 v38, v32
	v_cvt_f32_i32_e32 v37, v31
	v_cvt_f32_i32_e32 v36, v30
	v_mad_i64_i32 v[30:31], s[0:1], v40, s78, v[34:35]
	v_cvt_f32_i32_e32 v41, v27
	v_cvt_f32_i32_e32 v43, v29
	v_cvt_f32_i32_e32 v42, v28
	v_cvt_f32_i32_e32 v40, v26
	v_pk_mul_f32 v[34:35], v[8:9], v[38:39]
	v_mov_b32_e32 v38, v237
	v_pk_mul_f32 v[36:37], v[6:7], v[36:37]
	v_pk_mul_f32 v[26:27], v[34:35], v[38:39] op_sel_hi:[1,0]
	v_pk_mul_f32 v[34:35], v[4:5], v[42:43]
	v_pk_mul_f32 v[40:41], v[2:3], v[40:41]
	v_lshl_add_u64 v[32:33], v[146:147], 1, v[30:31]
	v_pk_mul_f32 v[28:29], v[36:37], v[38:39] op_sel_hi:[1,0]
	v_pk_mul_f32 v[36:37], v[34:35], v[38:39] op_sel_hi:[1,0]
	v_pk_mul_f32 v[34:35], v[40:41], v[38:39] op_sel_hi:[1,0]
	s_and_b64 vcc, exec, s[6:7]
	s_mov_b64 s[0:1], -1
	v_cvt_pk_bf16_f32 v38, v28, v29
	v_cvt_pk_bf16_f32 v39, v26, v27
	v_cvt_pk_bf16_f32 v40, v34, v35
	v_cvt_pk_bf16_f32 v41, v36, v37
	s_mov_b64 s[0:1], 0
	global_store_dwordx4 v[32:33], v[38:41], off
	s_andn2_b64 vcc, exec, s[0:1]
	v_cvt_f32_i32_e32 v23, v23
	v_cvt_f32_i32_e32 v22, v22
	v_cvt_f32_i32_e32 v25, v25
	v_cvt_f32_i32_e32 v24, v24
	v_cvt_f32_i32_e32 v35, v19
	v_cvt_f32_i32_e32 v37, v21
	v_cvt_f32_i32_e32 v36, v20
	v_cvt_f32_i32_e32 v34, v18
	v_mov_b32_e32 v26, v237
	v_mov_b32_e32 v27, v237
	v_pk_mul_f32 v[22:23], v[14:15], v[22:23]
	v_pk_mul_f32 v[24:25], v[16:17], v[24:25]
	v_mov_b32_e32 v28, v237
	v_mov_b32_e32 v29, v237
	v_pk_mul_f32 v[20:21], v[22:23], v[26:27]
	v_pk_mul_f32 v[22:23], v[12:13], v[36:37]
	v_pk_mul_f32 v[34:35], v[10:11], v[34:35]
	v_pk_mul_f32 v[18:19], v[24:25], v[28:29]
	v_pk_mul_f32 v[24:25], v[22:23], v[28:29]
	v_pk_mul_f32 v[22:23], v[34:35], v[26:27]
	s_and_b64 vcc, exec, s[6:7]
	s_mov_b64 s[0:1], -1
	v_cvt_pk_bf16_f32 v26, v20, v21
	v_cvt_pk_bf16_f32 v27, v18, v19
	v_cvt_pk_bf16_f32 v28, v22, v23
	v_cvt_pk_bf16_f32 v29, v24, v25
	global_store_dwordx4 v[32:33], v[26:29], off offset:256
	s_branch .Lg1join_0

;     __device__ __forceinline__ void operator()(const f32x4 (&acc)[2][2][4][2], const Pre& p, const Unit& u, int wr, int wc, int fr, int fq) const {
;         asm volatile("" : "+v"(fr), "+v"(fq));
;         const int row0 = u.pm * BM + wr * 64 + fr, col0 = u.pn * BM + wc * 32 + 8 * fq;
;         const bool glu = (u.pn * BM >= ZB) && (u.pn * BM < ZQ);
; #pragma unroll
;         for (int ai = 0; ai < 2; ++ai)
; #pragma unroll
;             for (int m = 0; m < 4; ++m) { bf16_t* rowp = O + (size_t)(row0 + ai * HALF + m * 16) * ldc;
;                 const float rs = p.rs[ai * 4 + m];
; #pragma unroll
;                 for (int bj = 0; bj < 2; ++bj) {
;                     const f32x4 v0 = (__builtin_convertvector(__builtin_bit_cast(i32x4, acc[ai][bj][m][0]), f32x4) * p.wv[bj][0]) * rs, v1 = (__builtin_convertvector(__builtin_bit_cast(i32x4, acc[ai][bj][m][1]), f32x4) * p.wv[bj][1]) * rs;
;                     if (glu) {
.LBB0_140:
	v_mov_b32_e32 v147, v1
	v_mov_b32_e32 v146, v250
	s_or_b32 s0, s41, s71
	v_lshl_add_u32 v146, v146, 3, s0
	s_add_i32 s0, s6, -1
	v_cvt_f32_i32_e32 v153, v145
	v_cvt_f32_i32_e32 v152, v144
	s_cmp_gt_u32 s0, 1
	s_cselect_b64 s[0:1], -1, 0
	s_add_i32 s33, s33, s70
	v_add_u32_e32 v154, s33, v147
	v_mov_b64_e32 v[148:149], s[28:29]
	v_cvt_f32_i32_e32 v151, v143
	v_cvt_f32_i32_e32 v150, v142
	v_mad_i64_i32 v[142:143], s[2:3], v154, s78, v[148:149]
	s_waitcnt vmcnt(0)
	v_pk_mul_f32 v[148:149], v[8:9], v[152:153]
	v_cvt_f32_i32_e32 v139, v139
	v_cvt_f32_i32_e32 v153, v141
	v_cvt_f32_i32_e32 v152, v140
	v_cvt_f32_i32_e32 v138, v138
	v_pk_mul_f32 v[150:151], v[6:7], v[150:151]
	v_ashrrev_i32_e32 v147, 31, v146
	v_pk_mul_f32 v[140:141], v[148:149], v[226:227] op_sel_hi:[1,0]
	v_pk_mul_f32 v[148:149], v[150:151], v[226:227] op_sel_hi:[1,0]
	v_pk_mul_f32 v[150:151], v[4:5], v[152:153]
	v_pk_mul_f32 v[138:139], v[2:3], v[138:139]
	v_lshl_add_u64 v[144:145], v[146:147], 1, v[142:143]
	v_pk_mul_f32 v[152:153], v[150:151], v[226:227] op_sel_hi:[1,0]
	v_pk_mul_f32 v[150:151], v[138:139], v[226:227] op_sel_hi:[1,0]
	s_mov_b64 s[2:3], -1
	s_and_b64 vcc, exec, s[0:1]
	v_readlane_b32 s88, v255, 5
	s_cbranch_vccnz .Lg1plain_0
	s_nop 0
	s_cbranch_vccz .LBB0_142
	v_cvt_pk_bf16_f32 v156, v148, v149
	v_cvt_pk_bf16_f32 v157, v140, v141
	v_cvt_pk_bf16_f32 v158, v150, v151
	v_cvt_pk_bf16_f32 v159, v152, v153
	global_store_dwordx4 v[144:145], v[156:159], off
	s_mov_b64 s[2:3], 0

; template <class Epi, class Sched, class Gemm, bool ALIGN_EPI = false, bool SP2 = false>
; __device__ __forceinline__ void gemm_phase(PG8_LAS unsigned char* lds, const Gemm g, const Sched& S, const Epi& E) {
;     ...
;         else if constexpr (!Epi::AFTER_DRAIN) { E(acc, cur, wr, wc, fr, fq); S.done(cur); }
;         if (!has_next) break;
.Lg1join_0:
	s_cbranch_execz .LBB0_204
